# diff-attn loop: tmax computed with scalar v_mul/v_fma instead of op_sel packed ops (no s_nop pads), three redundant vmcnt(0) waits removed
# baseline (speedup 1.0000x reference)
; DI void diff_unit(unsigned char* smem, const bf16* __restrict__ QKV, bf16* __restrict__ Y, int h, int qb, float lam, float outscale, const float* __restrict__ gain, float kn0, float kn1, int tid) {
;     ...
;     for (int it = 0;; ++it, j -= 2) {
;         const int bufo = (it & 1) * D3_BUF;
;         asm volatile("s_waitcnt vmcnt(0)" ::: "memory");
;         __syncthreads();
;         if (it > 0 && flag[(it - 1) % 3] == 0u) break;
;         if (tid == 0) flag[(it + 1) % 3] = 0u;
;         const bool mine_next = (j - 2 >= 0);
;         if (mine_next) D3_DMA(j - 2, D3_BUF - bufo);
.LBB0_204:
	s_mul_hi_u32 s10, s66, 0xaaaaaaab
	s_lshr_b32 s10, s10, 1
	s_mul_i32 s10, s10, -12
	s_add_i32 s10, s76, s10
	v_mov_b32_e32 v34, s10
	v_mov_b32_e32 v35, s41
	s_waitcnt vmcnt(0) lgkmcnt(0)
	s_barrier
	ds_read_b32 v34, v34
	v_add_u32_e32 v192, -2, v85
	s_waitcnt lgkmcnt(0)
	v_cmp_ne_u32_e32 vcc, 0, v34
	v_cmp_eq_u32_e64 s[10:11], 0, v34
	s_and_saveexec_b64 s[48:49], vcc
	s_cbranch_execz .LBB0_203
	s_and_saveexec_b64 s[12:13], s[6:7]
	s_cbranch_execz .LBB0_207
	s_mul_hi_u32 s14, s65, 0xaaaaaaab
	s_lshr_b32 s14, s14, 1
	s_mul_i32 s14, s14, -12
	s_add_i32 s14, s80, s14
	v_mov_b32_e32 v34, s14
	v_mov_b32_e32 v35, s41
	ds_write_b32 v34, v33

; __device__ __forceinline__ float max_x32(float v) { auto rr = __builtin_amdgcn_permlane32_swap(__float_as_uint(v), __float_as_uint(v), false, false); return __builtin_fmaxf(__uint_as_float(rr[0]), __uint_as_float(rr[1])); }
; DI void diff_unit(unsigned char* smem, const bf16* __restrict__ QKV, bf16* __restrict__ Y, int h, int qb, float lam, float outscale, const float* __restrict__ gain, float kn0, float kn1, int tid) {
;     ...
;             if (j < qb) {
;                 float mx = p[0][0];
; #pragma unroll
;                 for (int kh = 0; kh < 2; ++kh)
; #pragma unroll
;                     for (int r = 0; r < 16; ++r) mx = __builtin_fmaxf(mx, p[kh][r]);
;                 float tmax = mx * c1 + slope2 * dq;
;                 tmax = max_x32(tmax);
;                 const float m_new = __builtin_fmaxf(m_run, tmax);
;                 if (__any(m_new > m_run)) {
;                     const float alpha = __builtin_amdgcn_exp2f(m_run - m_new);
;                     l_run *= alpha;
; #pragma unroll
;                     for (int dt = 0; dt < 4; ++dt)
; #pragma unroll
;                         for (int r = 0; r < 16; ++r) o[dt][r] *= alpha;
;                     m_run = m_new;
;                 }
.LBB0_214:
	s_andn2_saveexec_b64 s[16:17], s[16:17]
	s_cbranch_execz .LBB0_219
	s_nop 5
	v_max_f32_e32 v34, v81, v81
	v_max_f32_e32 v35, v80, v80
	v_max_f32_e32 v34, v35, v34
	v_max3_f32 v34, v34, v82, v83
	v_max3_f32 v34, v34, v84, v85
	v_max3_f32 v34, v34, v86, v87
	v_max3_f32 v34, v34, v88, v89
	v_max3_f32 v34, v34, v90, v91
	v_max3_f32 v34, v34, v92, v93
	v_max3_f32 v34, v34, v94, v95
	v_max3_f32 v34, v34, v96, v97
	v_max3_f32 v34, v34, v98, v99
	v_max3_f32 v34, v34, v100, v101
	v_max3_f32 v34, v34, v102, v103
	v_cvt_f32_i32_e32 v170, v161
	v_max3_f32 v34, v34, v104, v105
	v_max3_f32 v34, v34, v106, v107
	v_max3_f32 v34, v34, v108, v109
	v_max3_f32 v161, v34, v110, v111
	v_mul_f32_e32 v34, v160, v170
	v_mul_f32_e32 v35, v161, v171
	v_fma_f32 v36, v160, v170, v35
	v_mov_b32_e32 v35, v36
	s_nop 1
	v_permlane32_swap_b32_e32 v36, v35
	v_max3_f32 v159, v163, v36, v35
	v_cmp_gt_f32_e32 vcc, v159, v163
	s_cbranch_vccz .LBB0_217
	v_sub_f32_e32 v35, v163, v159
	v_exp_f32_e32 v36, v35
	s_nop 0
	v_pk_mul_f32 v[78:79], v[78:79], v[36:37] op_sel_hi:[1,0]
	v_pk_mul_f32 v[76:77], v[76:77], v[36:37] op_sel_hi:[1,0]
	v_pk_mul_f32 v[74:75], v[74:75], v[36:37] op_sel_hi:[1,0]
	v_pk_mul_f32 v[72:73], v[72:73], v[36:37] op_sel_hi:[1,0]
	v_pk_mul_f32 v[70:71], v[70:71], v[36:37] op_sel_hi:[1,0]
	v_pk_mul_f32 v[68:69], v[68:69], v[36:37] op_sel_hi:[1,0]
	v_pk_mul_f32 v[66:67], v[66:67], v[36:37] op_sel_hi:[1,0]
	v_pk_mul_f32 v[64:65], v[64:65], v[36:37] op_sel_hi:[1,0]
	v_pk_mul_f32 v[62:63], v[62:63], v[36:37] op_sel_hi:[1,0]
	v_pk_mul_f32 v[60:61], v[60:61], v[36:37] op_sel_hi:[1,0]
	v_pk_mul_f32 v[58:59], v[58:59], v[36:37] op_sel_hi:[1,0]
	v_pk_mul_f32 v[56:57], v[56:57], v[36:37] op_sel_hi:[1,0]
	v_pk_mul_f32 v[54:55], v[54:55], v[36:37] op_sel_hi:[1,0]
	v_pk_mul_f32 v[52:53], v[52:53], v[36:37] op_sel_hi:[1,0]
	v_pk_mul_f32 v[50:51], v[50:51], v[36:37] op_sel_hi:[1,0]
	v_pk_mul_f32 v[48:49], v[48:49], v[36:37] op_sel_hi:[1,0]
	v_pk_mul_f32 v[30:31], v[30:31], v[36:37] op_sel_hi:[1,0]
	v_pk_mul_f32 v[28:29], v[28:29], v[36:37] op_sel_hi:[1,0]
	v_pk_mul_f32 v[26:27], v[26:27], v[36:37] op_sel_hi:[1,0]
	v_pk_mul_f32 v[24:25], v[24:25], v[36:37] op_sel_hi:[1,0]
	v_pk_mul_f32 v[22:23], v[22:23], v[36:37] op_sel_hi:[1,0]
	v_pk_mul_f32 v[20:21], v[20:21], v[36:37] op_sel_hi:[1,0]
	v_pk_mul_f32 v[18:19], v[18:19], v[36:37] op_sel_hi:[1,0]
	v_pk_mul_f32 v[16:17], v[16:17], v[36:37] op_sel_hi:[1,0]
	v_pk_mul_f32 v[14:15], v[14:15], v[36:37] op_sel_hi:[1,0]
	v_pk_mul_f32 v[12:13], v[12:13], v[36:37] op_sel_hi:[1,0]
	v_pk_mul_f32 v[10:11], v[10:11], v[36:37] op_sel_hi:[1,0]
	v_pk_mul_f32 v[8:9], v[8:9], v[36:37] op_sel_hi:[1,0]
	v_pk_mul_f32 v[6:7], v[6:7], v[36:37] op_sel_hi:[1,0]
	v_pk_mul_f32 v[4:5], v[4:5], v[36:37] op_sel_hi:[1,0]
	v_pk_mul_f32 v[2:3], v[2:3], v[36:37] op_sel_hi:[1,0]
	v_pk_mul_f32 v[0:1], v[0:1], v[36:37] op_sel_hi:[1,0]
	v_mul_f32_e32 v162, v162, v36
	s_branch .LBB0_218
